# attention softmax: mask test via v_bfe_i32+v_bfi_b32 instead of and+cmp+cndmask (bit-exact), dropped canonicalize pairs; S5 KM batch loads
# speedup vs baseline: 1.0134x; 1.0042x over previous
.LBB0_2335:
	s_add_i32 s10, s7, -2
	s_and_b32 s16, s10, 3
	s_add_i32 s10, s9, -3
	s_cmp_lt_i32 s7, s64
	s_cselect_b32 s12, s10, 0
	s_cselect_b32 s13, s7, s42
	s_and_b64 s[10:11], s[40:41], exec
	s_cselect_b32 s12, s12, s13
	s_ashr_i32 s13, s12, 31
	s_lshl_b64 s[10:11], s[12:13], 18
	s_add_u32 s10, s60, s10
	s_addc_u32 s11, s61, s11
	s_and_b32 s14, s6, 0x18000
	s_xor_b32 s17, s14, 0x10000
	s_lshl_b64 s[14:15], s[12:13], 7
	s_add_u32 s14, s39, s14
	s_addc_u32 s15, s62, s15
	s_add_i32 s17, s63, s17
	s_waitcnt vmcnt(5) lgkmcnt(0)
	s_barrier
	v_lshl_add_u32 v66, s16, 11, v153
	s_mov_b32 m0, s17
	ds_read_b64 v[158:159], v66
	global_load_lds_dwordx4 v152, s[10:11]
	v_lshl_add_u64 v[66:67], v[0:1], 1, s[14:15]
	s_add_i32 m0, s17, 0x4000
	s_lshl_b64 s[12:13], s[12:13], 16
	global_load_lds_dwordx4 v[66:67], off
	s_add_i32 m0, s17, 0x400
	v_lshl_add_u64 v[66:67], v[142:143], 1, s[14:15]
	global_load_lds_dwordx4 v154, s[10:11]
	s_lshl_b32 s10, s16, 15
	s_add_i32 m0, s17, 0x4400
	s_add_i32 s10, s10, 0
	global_load_lds_dwordx4 v[66:67], off
	v_add_u32_e32 v76, s10, v149
	ds_read_b128 v[66:69], v76
	v_add_u32_e32 v77, s10, v165
	ds_read_b128 v[70:73], v77
	s_waitcnt lgkmcnt(0)
	v_mfma_f32_32x32x16_bf16 v[82:97], v[66:69], v[98:101], 0
	v_add_u32_e32 v155, s10, v166
	ds_read_b128 v[66:69], v155
	v_add_u32_e32 v157, s10, v167
	v_add_u32_e32 v179, s10, v168
	s_and_b32 s11, s8, 0x1800
	s_xor_b32 s11, s11, 0x1000
	v_lshl_add_u64 v[74:75], v[150:151], 0, s[12:13]
	v_mfma_f32_32x32x16_bf16 v[82:97], v[70:73], v[102:105], v[82:97]
	ds_read_b128 v[70:73], v157
	s_add_i32 m0, s43, s11
	v_add_u32_e32 v204, s10, v169
	global_load_lds_dword v[74:75], off
	v_add_u32_e32 v208, s10, v170
	v_add_u32_e32 v212, s10, v171
	s_waitcnt lgkmcnt(0)
	v_mfma_f32_32x32x16_bf16 v[82:97], v[66:69], v[106:109], v[82:97]
	ds_read_b128 v[66:69], v179
	v_mfma_f32_32x32x16_bf16 v[82:97], v[70:73], v[110:113], v[82:97]
	ds_read_b128 v[70:73], v204
	ds_read_b128 v[180:183], v208
	ds_read_b128 v[184:187], v212
	s_waitcnt lgkmcnt(0)
	v_mfma_f32_32x32x16_bf16 v[82:97], v[66:69], v[114:117], v[82:97]
	ds_read_b128 v[66:69], v76 offset:8192
	ds_read_b128 v[188:191], v77 offset:8192
	ds_read_b128 v[192:195], v155 offset:8192
	ds_read_b128 v[196:199], v157 offset:8192
	ds_read_b128 v[200:203], v179 offset:8192
	ds_read_b128 v[204:207], v204 offset:8192
	ds_read_b128 v[208:211], v208 offset:8192
	ds_read_b128 v[212:215], v212 offset:8192
	v_mfma_f32_32x32x16_bf16 v[82:97], v[70:73], v[118:121], v[82:97]
	s_waitcnt lgkmcnt(0)
	v_mfma_f32_32x32x16_bf16 v[66:81], v[66:69], v[98:101], 0
	v_mfma_f32_32x32x16_bf16 v[66:81], v[188:191], v[102:105], v[66:81]
	v_mfma_f32_32x32x16_bf16 v[82:97], v[180:183], v[122:125], v[82:97]
	v_lshrrev_b32_e32 v181, v132, v158
	v_bfe_i32 v155, v181, 1, 1
	v_bfe_i32 v157, v181, 0, 1
	v_bfe_i32 v179, v181, 3, 1
	v_bfe_i32 v216, v181, 2, 1
	v_mfma_f32_32x32x16_bf16 v[66:81], v[192:195], v[106:109], v[66:81]
	v_mfma_f32_32x32x16_bf16 v[82:97], v[184:187], v[126:129], v[82:97]
	v_mfma_f32_32x32x16_bf16 v[66:81], v[196:199], v[110:113], v[66:81]
	s_nop 10
	v_add_f32_e64 v82, v82, -v156
	v_add_f32_e64 v83, v83, -v156
	v_add_f32_e64 v84, v84, -v156
	v_add_f32_e64 v85, v85, -v156
	v_bfi_b32 v155, v155, v83, v177
	v_bfi_b32 v158, v157, v82, v177
	v_mfma_f32_32x32x16_bf16 v[66:81], v[200:203], v[114:117], v[66:81]
	v_max3_f32 v82, v158, s55, v155
	v_bfi_b32 v157, v179, v85, v177
	v_bfe_i32 v180, v181, 8, 1
	v_bfi_b32 v179, v216, v84, v177
	v_max3_f32 v83, v82, v179, v157
	v_bfe_i32 v82, v181, 9, 1
	v_pk_add_f32 v[84:85], v[86:87], v[156:157] op_sel_hi:[1,0] neg_lo:[0,1] neg_hi:[0,1]
	v_bfe_i32 v86, v181, 11, 1
	v_bfe_i32 v87, v181, 10, 1
	v_bfi_b32 v82, v82, v85, v177
	v_mfma_f32_32x32x16_bf16 v[66:81], v[204:207], v[118:121], v[66:81]
	v_bfi_b32 v180, v180, v84, v177
	v_add_f32_e64 v84, v88, -v156
	v_add_f32_e64 v85, v89, -v156
	v_max3_f32 v83, v83, v180, v82
	v_pk_add_f32 v[88:89], v[90:91], v[156:157] op_sel_hi:[1,0] neg_lo:[0,1] neg_hi:[0,1]
	v_bfi_b32 v85, v86, v85, v177
	v_bfe_i32 v217, v181, 18, 1
	v_mfma_f32_32x32x16_bf16 v[66:81], v[208:211], v[122:125], v[66:81]
	v_bfi_b32 v87, v87, v84, v177
	v_max3_f32 v86, v83, v87, v85
	v_bfe_i32 v83, v181, 17, 1
	v_bfe_i32 v84, v181, 16, 1
	v_bfi_b32 v83, v83, v89, v177
	v_mfma_f32_32x32x16_bf16 v[66:81], v[212:215], v[126:129], v[66:81]
	v_bfi_b32 v84, v84, v88, v177
	v_max3_f32 v90, v86, v84, v83
	v_bfe_i32 v86, v181, 19, 1
	v_add_f32_e64 v88, v92, -v156
	v_add_f32_e64 v89, v93, -v156
	v_pk_add_f32 v[92:93], v[94:95], v[156:157] op_sel_hi:[1,0] neg_lo:[0,1] neg_hi:[0,1]
	v_pk_add_f32 v[94:95], v[96:97], v[156:157] op_sel_hi:[1,0] neg_lo:[0,1] neg_hi:[0,1]
	v_bfi_b32 v86, v86, v89, v177
	v_bfe_i32 v218, v181, 24, 1
	v_bfi_b32 v88, v217, v88, v177
	v_max3_f32 v89, v90, v88, v86
	v_bfe_i32 v90, v181, 25, 1
	v_bfi_b32 v90, v90, v93, v177
	v_bfe_i32 v91, v181, 26, 1
	v_bfi_b32 v92, v218, v92, v177
	v_max3_f32 v93, v89, v92, v90
	v_bfe_i32 v89, v181, 27, 1
	v_bfi_b32 v89, v89, v95, v177
	v_bfi_b32 v91, v91, v94, v177
	v_max3_f32 v93, v93, v91, v89
	v_mov_b32_e32 v94, v93
	s_nop 1
	v_permlane32_swap_b32_e32 v93, v94
	v_max_f32_e32 v93, v93, v94
	v_cmp_lt_f32_e32 vcc, s56, v93
	s_cbranch_vccz .LBB0_2337
	s_nop 0
	v_cndmask_b32_e32 v93, 0, v93, vcc
	v_exp_f32_e64 v94, -v93
	v_add_f32_e32 v156, v156, v93
	v_sub_f32_e32 v158, v158, v93
	v_sub_f32_e32 v155, v155, v93
	v_pk_mul_f32 v[64:65], v[64:65], v[94:95] op_sel_hi:[1,0]
	v_pk_mul_f32 v[62:63], v[62:63], v[94:95] op_sel_hi:[1,0]
	v_pk_mul_f32 v[60:61], v[60:61], v[94:95] op_sel_hi:[1,0]
	v_pk_mul_f32 v[58:59], v[58:59], v[94:95] op_sel_hi:[1,0]
	v_pk_mul_f32 v[56:57], v[56:57], v[94:95] op_sel_hi:[1,0]
	v_pk_mul_f32 v[54:55], v[54:55], v[94:95] op_sel_hi:[1,0]
	v_pk_mul_f32 v[52:53], v[52:53], v[94:95] op_sel_hi:[1,0]
	v_pk_mul_f32 v[50:51], v[50:51], v[94:95] op_sel_hi:[1,0]
	v_pk_mul_f32 v[48:49], v[48:49], v[94:95] op_sel_hi:[1,0]
	v_pk_mul_f32 v[46:47], v[46:47], v[94:95] op_sel_hi:[1,0]
	v_pk_mul_f32 v[44:45], v[44:45], v[94:95] op_sel_hi:[1,0]
	v_pk_mul_f32 v[42:43], v[42:43], v[94:95] op_sel_hi:[1,0]
	v_pk_mul_f32 v[40:41], v[40:41], v[94:95] op_sel_hi:[1,0]
	v_pk_mul_f32 v[38:39], v[38:39], v[94:95] op_sel_hi:[1,0]
	v_pk_mul_f32 v[36:37], v[36:37], v[94:95] op_sel_hi:[1,0]
	v_pk_mul_f32 v[34:35], v[34:35], v[94:95] op_sel_hi:[1,0]
	v_pk_mul_f32 v[32:33], v[32:33], v[94:95] op_sel_hi:[1,0]
	v_pk_mul_f32 v[30:31], v[30:31], v[94:95] op_sel_hi:[1,0]
	v_pk_mul_f32 v[28:29], v[28:29], v[94:95] op_sel_hi:[1,0]
	v_pk_mul_f32 v[26:27], v[26:27], v[94:95] op_sel_hi:[1,0]
	v_pk_mul_f32 v[24:25], v[24:25], v[94:95] op_sel_hi:[1,0]
	v_pk_mul_f32 v[22:23], v[22:23], v[94:95] op_sel_hi:[1,0]
	v_pk_mul_f32 v[20:21], v[20:21], v[94:95] op_sel_hi:[1,0]
	v_pk_mul_f32 v[18:19], v[18:19], v[94:95] op_sel_hi:[1,0]
	v_pk_mul_f32 v[16:17], v[16:17], v[94:95] op_sel_hi:[1,0]
	v_pk_mul_f32 v[14:15], v[14:15], v[94:95] op_sel_hi:[1,0]
	v_pk_mul_f32 v[12:13], v[12:13], v[94:95] op_sel_hi:[1,0]
	v_pk_mul_f32 v[10:11], v[10:11], v[94:95] op_sel_hi:[1,0]
	v_pk_mul_f32 v[8:9], v[8:9], v[94:95] op_sel_hi:[1,0]
	v_pk_mul_f32 v[6:7], v[6:7], v[94:95] op_sel_hi:[1,0]
	v_pk_mul_f32 v[4:5], v[4:5], v[94:95] op_sel_hi:[1,0]
	v_pk_mul_f32 v[2:3], v[2:3], v[94:95] op_sel_hi:[1,0]
	v_sub_f32_e32 v179, v179, v93
	v_sub_f32_e32 v157, v157, v93
	v_sub_f32_e32 v180, v180, v93
	v_sub_f32_e32 v82, v82, v93
	v_sub_f32_e32 v87, v87, v93
	v_sub_f32_e32 v85, v85, v93
	v_sub_f32_e32 v84, v84, v93
	v_sub_f32_e32 v83, v83, v93
	v_sub_f32_e32 v88, v88, v93
	v_sub_f32_e32 v86, v86, v93
	v_sub_f32_e32 v92, v92, v93
	v_sub_f32_e32 v90, v90, v93
	v_sub_f32_e32 v91, v91, v93
	v_sub_f32_e32 v89, v89, v93
	v_mul_f32_e32 v139, v139, v94
.LBB0_2337:
	v_add_u32_e32 v93, s10, v147
	ds_read_b128 v[94:97], v93 offset:16384
	ds_read_b128 v[184:187], v93 offset:20480
	v_exp_f32_e32 v158, v158
	v_exp_f32_e32 v155, v155
	v_exp_f32_e32 v179, v179
	v_exp_f32_e32 v188, v157
	v_exp_f32_e32 v189, v180
	v_exp_f32_e32 v190, v82
	v_exp_f32_e32 v191, v87
	v_exp_f32_e32 v192, v85
	v_cvt_pk_bf16_f32 v180, v158, v155
	v_cvt_pk_bf16_f32 v181, v179, v188
	v_cvt_pk_bf16_f32 v182, v189, v190
	v_cvt_pk_bf16_f32 v183, v191, v192
	v_add_u32_e32 v193, s10, v172
	v_mov_b32_e32 v157, v156
	s_waitcnt lgkmcnt(0)
	v_mfma_f32_32x32x16_bf16 v[50:65], v[94:97], v[180:183], v[50:65]
	ds_read_b128 v[94:97], v93 offset:24576
	v_add_f32_e64 v66, v66, -v156
	v_add_f32_e64 v67, v67, -v157
	v_add_f32_e64 v74, v74, -v156
	v_add_f32_e64 v75, v75, -v157
	v_mfma_f32_32x32x16_bf16 v[34:49], v[184:187], v[180:183], v[34:49]
	v_exp_f32_e32 v184, v84
	v_exp_f32_e32 v185, v83
	ds_read_b128 v[82:85], v93 offset:28672
	v_exp_f32_e32 v186, v92
	v_exp_f32_e32 v187, v90
	v_add_f32_e32 v90, 0, v158
	s_waitcnt lgkmcnt(0)
	v_mfma_f32_32x32x16_bf16 v[18:33], v[94:97], v[180:183], v[18:33]
	ds_read_b128 v[92:95], v193 offset:16384
	v_exp_f32_e32 v96, v88
	v_exp_f32_e32 v97, v86
	v_add_f32_e32 v90, v155, v90
	v_add_f32_e32 v90, v179, v90
	v_add_f32_e32 v90, v188, v90
	v_add_f32_e32 v90, v189, v90
	v_mfma_f32_32x32x16_bf16 v[2:17], v[82:85], v[180:183], v[2:17]
	v_exp_f32_e32 v181, v89
	ds_read_b128 v[86:89], v193 offset:20480
	v_exp_f32_e32 v180, v91
	v_cvt_pk_bf16_f32 v82, v184, v185
	v_cvt_pk_bf16_f32 v83, v96, v97
	v_cvt_pk_bf16_f32 v84, v186, v187
	v_cvt_pk_bf16_f32 v85, v180, v181
	s_waitcnt lgkmcnt(0)
	s_nop 0
	v_mfma_f32_32x32x16_bf16 v[50:65], v[92:95], v[82:85], v[50:65]
	v_add_f32_e32 v94, v190, v90
	ds_read_b128 v[90:93], v193 offset:24576
	v_mfma_f32_32x32x16_bf16 v[34:49], v[86:89], v[82:85], v[34:49]
	v_add_f32_e32 v86, v191, v94
	v_add_f32_e32 v86, v192, v86
	v_add_f32_e32 v86, v184, v86
	v_add_f32_e32 v86, v185, v86
	v_add_f32_e32 v86, v96, v86
	v_add_f32_e32 v94, v97, v86
	ds_read_b128 v[86:89], v193 offset:28672
	s_waitcnt lgkmcnt(0)
	v_mfma_f32_32x32x16_bf16 v[18:33], v[90:93], v[82:85], v[18:33]
	v_lshrrev_b32_e32 v91, v132, v159
	v_bfe_i32 v92, v91, 1, 1
	v_add_f32_e32 v90, v186, v94
	v_add_f32_e32 v90, v187, v90
	v_add_f32_e32 v90, v180, v90
	v_mfma_f32_32x32x16_bf16 v[2:17], v[86:89], v[82:85], v[2:17]
	v_bfe_i32 v83, v91, 0, 1
	v_bfi_b32 v82, v92, v67, v177
	v_bfe_i32 v84, v91, 3, 1
	v_bfe_i32 v85, v91, 2, 1
	v_bfi_b32 v83, v83, v66, v177
	v_pk_add_f32 v[66:67], v[68:69], v[156:157] neg_lo:[0,1] neg_hi:[0,1]
	v_max3_f32 v86, v83, s55, v82
	v_bfe_i32 v69, v91, 9, 1
	v_bfi_b32 v84, v84, v67, v177
	v_add_f32_e32 v90, v181, v90
	v_bfi_b32 v85, v85, v66, v177
	v_max3_f32 v68, v86, v85, v84
	v_bfe_i32 v86, v91, 8, 1
	v_pk_add_f32 v[66:67], v[70:71], v[156:157] neg_lo:[0,1] neg_hi:[0,1]
	v_bfe_i32 v70, v91, 11, 1
	v_bfe_i32 v219, v91, 10, 1
	v_bfi_b32 v67, v69, v67, v177
	v_bfi_b32 v86, v86, v66, v177
	v_max3_f32 v66, v68, v86, v67
	v_pk_add_f32 v[68:69], v[72:73], v[156:157] neg_lo:[0,1] neg_hi:[0,1]
	v_bfe_i32 v73, v91, 18, 1
	v_bfi_b32 v70, v70, v69, v177
	v_bfe_i32 v69, v91, 16, 1
	v_bfe_i32 v71, v91, 19, 1
	v_bfi_b32 v72, v219, v68, v177
	v_bfe_i32 v68, v91, 17, 1
	v_max3_f32 v66, v66, v72, v70
	v_bfi_b32 v68, v68, v75, v177
	v_bfi_b32 v69, v69, v74, v177
	v_pk_add_f32 v[74:75], v[76:77], v[156:157] neg_lo:[0,1] neg_hi:[0,1]
	v_bfe_i32 v220, v91, 25, 1
	v_bfe_i32 v77, v91, 24, 1
	v_bfi_b32 v71, v71, v75, v177
	v_max3_f32 v66, v66, v69, v68
	v_bfi_b32 v73, v73, v74, v177
	v_pk_add_f32 v[74:75], v[78:79], v[156:157] neg_lo:[0,1] neg_hi:[0,1]
	v_bfe_i32 v76, v91, 26, 1
	v_pk_add_f32 v[78:79], v[80:81], v[156:157] neg_lo:[0,1] neg_hi:[0,1]
	v_bfi_b32 v75, v220, v75, v177
	v_max3_f32 v66, v66, v73, v71
	v_bfi_b32 v77, v77, v74, v177
	v_bfe_i32 v74, v91, 27, 1
	v_max3_f32 v66, v66, v77, v75
	v_bfi_b32 v74, v74, v79, v177
	v_bfi_b32 v76, v76, v78, v177
	v_max3_f32 v78, v66, v76, v74
	v_mov_b32_e32 v79, v78
	s_nop 1
	v_permlane32_swap_b32_e32 v78, v79
	v_max_f32_e32 v78, v78, v79
	v_add_f32_e32 v66, v139, v90
	v_cmp_lt_f32_e32 vcc, s56, v78
	s_cbranch_vccz .LBB0_2334
	s_nop 0
	v_cndmask_b32_e32 v79, 0, v78, vcc
	v_exp_f32_e64 v78, -v79
	v_add_f32_e32 v156, v156, v79
	v_sub_f32_e32 v83, v83, v79
	v_sub_f32_e32 v82, v82, v79
	v_pk_mul_f32 v[64:65], v[64:65], v[78:79] op_sel_hi:[1,0]
	v_pk_mul_f32 v[62:63], v[62:63], v[78:79] op_sel_hi:[1,0]
	v_pk_mul_f32 v[60:61], v[60:61], v[78:79] op_sel_hi:[1,0]
	v_pk_mul_f32 v[58:59], v[58:59], v[78:79] op_sel_hi:[1,0]
	v_pk_mul_f32 v[56:57], v[56:57], v[78:79] op_sel_hi:[1,0]
	v_pk_mul_f32 v[54:55], v[54:55], v[78:79] op_sel_hi:[1,0]
	v_pk_mul_f32 v[52:53], v[52:53], v[78:79] op_sel_hi:[1,0]
	v_pk_mul_f32 v[50:51], v[50:51], v[78:79] op_sel_hi:[1,0]
	v_pk_mul_f32 v[48:49], v[48:49], v[78:79] op_sel_hi:[1,0]
	v_pk_mul_f32 v[46:47], v[46:47], v[78:79] op_sel_hi:[1,0]
	v_pk_mul_f32 v[44:45], v[44:45], v[78:79] op_sel_hi:[1,0]
	v_pk_mul_f32 v[42:43], v[42:43], v[78:79] op_sel_hi:[1,0]
	v_pk_mul_f32 v[40:41], v[40:41], v[78:79] op_sel_hi:[1,0]
	v_pk_mul_f32 v[38:39], v[38:39], v[78:79] op_sel_hi:[1,0]
	v_pk_mul_f32 v[36:37], v[36:37], v[78:79] op_sel_hi:[1,0]
	v_pk_mul_f32 v[34:35], v[34:35], v[78:79] op_sel_hi:[1,0]
	v_pk_mul_f32 v[32:33], v[32:33], v[78:79] op_sel_hi:[1,0]
	v_pk_mul_f32 v[30:31], v[30:31], v[78:79] op_sel_hi:[1,0]
	v_pk_mul_f32 v[28:29], v[28:29], v[78:79] op_sel_hi:[1,0]
	v_pk_mul_f32 v[26:27], v[26:27], v[78:79] op_sel_hi:[1,0]
	v_pk_mul_f32 v[24:25], v[24:25], v[78:79] op_sel_hi:[1,0]
	v_pk_mul_f32 v[22:23], v[22:23], v[78:79] op_sel_hi:[1,0]
	v_pk_mul_f32 v[20:21], v[20:21], v[78:79] op_sel_hi:[1,0]
	v_pk_mul_f32 v[18:19], v[18:19], v[78:79] op_sel_hi:[1,0]
	v_pk_mul_f32 v[16:17], v[16:17], v[78:79] op_sel_hi:[1,0]
	v_pk_mul_f32 v[14:15], v[14:15], v[78:79] op_sel_hi:[1,0]
	v_pk_mul_f32 v[12:13], v[12:13], v[78:79] op_sel_hi:[1,0]
	v_pk_mul_f32 v[10:11], v[10:11], v[78:79] op_sel_hi:[1,0]
	v_pk_mul_f32 v[8:9], v[8:9], v[78:79] op_sel_hi:[1,0]
	v_pk_mul_f32 v[6:7], v[6:7], v[78:79] op_sel_hi:[1,0]
	v_pk_mul_f32 v[4:5], v[4:5], v[78:79] op_sel_hi:[1,0]
	v_pk_mul_f32 v[2:3], v[2:3], v[78:79] op_sel_hi:[1,0]
	v_sub_f32_e32 v85, v85, v79
	v_sub_f32_e32 v84, v84, v79
	v_sub_f32_e32 v86, v86, v79
	v_sub_f32_e32 v67, v67, v79
	v_sub_f32_e32 v72, v72, v79
	v_sub_f32_e32 v70, v70, v79
	v_sub_f32_e32 v69, v69, v79
	v_sub_f32_e32 v68, v68, v79
	v_sub_f32_e32 v73, v73, v79
	v_sub_f32_e32 v71, v71, v79
	v_sub_f32_e32 v77, v77, v79
	v_sub_f32_e32 v75, v75, v79
	v_sub_f32_e32 v76, v76, v79
	v_sub_f32_e32 v74, v74, v79
	v_mul_f32_e32 v66, v66, v78
	s_branch .LBB0_2334

.LBB0_2341:
	s_and_b64 vcc, exec, s[0:1]
	s_cbranch_vccnz .LBB0_2324
	s_or_b32 s10, s5, 0x400
	s_or_b32 s6, s59, 1
	s_and_b64 s[0:1], s[40:41], exec
	s_cselect_b32 s1, 0, 0
	s_cselect_b32 s0, s6, 2
	s_lshl_b64 s[6:7], s[0:1], 18
	s_add_u32 s6, s60, s6
	s_addc_u32 s7, s61, s7
	s_lshl_b64 s[8:9], s[0:1], 7
	s_add_u32 s8, s39, s8
	s_addc_u32 s9, s62, s9
	s_add_i32 s11, 0, 0x10000
	v_add_u32_e32 v96, s43, v161
	s_waitcnt vmcnt(5) lgkmcnt(0)
	s_barrier
	s_add_i32 m0, s11, s5
	ds_read_b64 v[34:35], v96
	global_load_lds_dwordx4 v152, s[6:7]
	v_lshl_add_u64 v[2:3], v[0:1], 1, s[8:9]
	s_add_i32 m0, s57, s5
	v_add_u32_e32 v40, 0, v149
	global_load_lds_dwordx4 v[2:3], off
	s_add_i32 m0, s11, s10
	v_lshl_add_u64 v[2:3], v[142:143], 1, s[8:9]
	global_load_lds_dwordx4 v154, s[6:7]
	s_add_i32 m0, s57, s10
	v_add_u32_e32 v41, 0, v165
	global_load_lds_dwordx4 v[2:3], off
	ds_read_b128 v[2:5], v40
	ds_read_b128 v[18:21], v41
	s_waitcnt vmcnt(0) lgkmcnt(0)
	v_mfma_f32_32x32x16_bf16 v[2:17], v[2:5], v[98:101], 0
	v_add_u32_e32 v46, 0, v166
	ds_read_b128 v[22:25], v46
	s_lshl_b64 s[0:1], s[0:1], 16
	s_add_i32 m0, s43, 0x1000
	v_add_u32_e32 v50, 0, v167
	v_add_u32_e32 v54, 0, v168
	v_add_u32_e32 v58, 0, v169
	v_mfma_f32_32x32x16_bf16 v[2:17], v[18:21], v[102:105], v[2:17]
	v_lshl_add_u64 v[18:19], v[150:151], 0, s[0:1]
	global_load_lds_dword v[18:19], off
	ds_read_b128 v[18:21], v50
	v_add_u32_e32 v62, 0, v170
	v_add_u32_e32 v66, 0, v171
	v_lshrrev_b32_e32 v70, v132, v34
	s_waitcnt lgkmcnt(0)
	v_mfma_f32_32x32x16_bf16 v[2:17], v[22:25], v[106:109], v[2:17]
	ds_read_b128 v[22:25], v54
	ds_read_b128 v[26:29], v58
	ds_read_b128 v[30:33], v62
	ds_read_b128 v[36:39], v66
	v_mfma_f32_32x32x16_bf16 v[2:17], v[18:21], v[110:113], v[2:17]
	ds_read_b128 v[18:21], v40 offset:8192
	ds_read_b128 v[42:45], v41 offset:8192
	ds_read_b128 v[46:49], v46 offset:8192
	ds_read_b128 v[50:53], v50 offset:8192
	ds_read_b128 v[54:57], v54 offset:8192
	ds_read_b128 v[58:61], v58 offset:8192
	ds_read_b128 v[62:65], v62 offset:8192
	ds_read_b128 v[66:69], v66 offset:8192
	s_waitcnt lgkmcnt(0)
	v_mfma_f32_32x32x16_bf16 v[2:17], v[22:25], v[114:117], v[2:17]
	v_bfe_i32 v22, v70, 1, 1
	v_bfe_i32 v221, v70, 0, 1
	v_mfma_f32_32x32x16_bf16 v[2:17], v[26:29], v[118:121], v[2:17]
	v_mfma_f32_32x32x16_bf16 v[2:17], v[30:33], v[122:125], v[2:17]
	v_mfma_f32_32x32x16_bf16 v[2:17], v[36:39], v[126:129], v[2:17]
	v_bfe_i32 v38, v70, 3, 1
	v_bfe_i32 v39, v70, 2, 1
	s_nop 9
	v_pk_add_f32 v[2:3], v[2:3], s[36:37] op_sel_hi:[1,0]
	v_bfi_b32 v34, v22, v3, v177
	v_mfma_f32_32x32x16_bf16 v[18:33], v[18:21], v[98:101], 0
	v_bfi_b32 v37, v221, v2, v177
	v_add_f32_e64 v2, v4, s36
	v_add_f32_e64 v3, v5, s36
	v_max3_f32 v36, v37, s55, v34
	v_bfe_i32 v222, v70, 9, 1
	v_bfi_b32 v40, v38, v3, v177
	v_mfma_f32_32x32x16_bf16 v[18:33], v[42:45], v[102:105], v[18:33]
	v_bfi_b32 v39, v39, v2, v177
	v_max3_f32 v4, v36, v39, v40
	v_bfe_i32 v36, v70, 8, 1
	v_add_f32_e64 v2, v6, s36
	v_add_f32_e64 v3, v7, s36
	v_mfma_f32_32x32x16_bf16 v[18:33], v[46:49], v[106:109], v[18:33]
	v_bfe_i32 v223, v70, 11, 1
	v_bfe_i32 v224, v70, 10, 1
	v_bfi_b32 v42, v222, v3, v177
	v_mfma_f32_32x32x16_bf16 v[18:33], v[50:53], v[110:113], v[18:33]
	v_bfi_b32 v41, v36, v2, v177
	v_add_f32_e64 v2, v8, s36
	v_add_f32_e64 v3, v9, s36
	v_bfe_i32 v225, v70, 17, 1
	v_max3_f32 v4, v4, v41, v42
	v_bfi_b32 v44, v223, v3, v177
	v_mfma_f32_32x32x16_bf16 v[18:33], v[54:57], v[114:117], v[18:33]
	v_bfe_i32 v226, v70, 16, 1
	v_bfi_b32 v43, v224, v2, v177
	v_add_f32_e64 v2, v10, s36
	v_add_f32_e64 v3, v11, s36
	v_bfe_i32 v227, v70, 19, 1
	v_max3_f32 v4, v4, v43, v44
	v_bfi_b32 v46, v225, v3, v177
	v_mfma_f32_32x32x16_bf16 v[18:33], v[58:61], v[118:121], v[18:33]
	v_bfe_i32 v228, v70, 18, 1
	v_bfi_b32 v45, v226, v2, v177
	v_add_f32_e64 v2, v12, s36
	v_add_f32_e64 v3, v13, s36
	v_bfe_i32 v229, v70, 25, 1
	v_mfma_f32_32x32x16_bf16 v[18:33], v[62:65], v[122:125], v[18:33]
	v_bfi_b32 v48, v227, v3, v177
	v_bfe_i32 v230, v70, 24, 1
	v_max3_f32 v4, v4, v45, v46
	v_bfi_b32 v47, v228, v2, v177
	v_pk_add_f32 v[2:3], v[14:15], s[36:37] op_sel_hi:[1,0]
	v_bfe_i32 v5, v70, 27, 1
	v_max3_f32 v4, v4, v47, v48
	v_bfi_b32 v50, v229, v3, v177
	v_bfe_i32 v6, v70, 26, 1
	v_mfma_f32_32x32x16_bf16 v[18:33], v[66:69], v[126:129], v[18:33]
	v_bfi_b32 v49, v230, v2, v177
	v_add_f32_e64 v2, v16, s36
	v_add_f32_e64 v3, v17, s36
	v_max3_f32 v4, v4, v49, v50
	v_bfi_b32 v52, v5, v3, v177
	v_bfi_b32 v51, v6, v2, v177
	v_max3_f32 v2, v4, v51, v52
	v_mov_b32_e32 v3, v2
	s_nop 1
	v_permlane32_swap_b32_e32 v2, v3
	v_max_f32_e32 v2, v2, v3
	v_cmp_lt_f32_e32 vcc, s56, v2
	s_cbranch_vccz .LBB0_2345
	s_nop 0
	v_cndmask_b32_e32 v36, 0, v2, vcc
	v_exp_f32_e64 v2, -v36
	v_add_f32_e32 v92, 0xc2200000, v36
	v_sub_f32_e32 v37, v37, v36
	v_sub_f32_e32 v34, v34, v36
	v_mul_f32_e32 v2, 0, v2
	v_mov_b32_e32 v3, v2
	v_mov_b32_e32 v4, v2
	v_mov_b32_e32 v5, v2
	v_mov_b32_e32 v6, v2
	v_mov_b32_e32 v7, v2
	v_mov_b32_e32 v8, v2
	v_mov_b32_e32 v9, v2
	v_mov_b32_e32 v10, v2
	v_mov_b32_e32 v11, v2
	v_mov_b32_e32 v12, v2
	v_mov_b32_e32 v13, v2
	v_mov_b32_e32 v14, v2
	v_mov_b32_e32 v15, v2
	v_mov_b32_e32 v16, v2
	v_mov_b32_e32 v17, v2
	v_sub_f32_e32 v39, v39, v36
	v_sub_f32_e32 v40, v40, v36
	v_sub_f32_e32 v41, v41, v36
	v_sub_f32_e32 v42, v42, v36
	v_sub_f32_e32 v43, v43, v36
	v_sub_f32_e32 v44, v44, v36
	v_sub_f32_e32 v45, v45, v36
	v_sub_f32_e32 v46, v46, v36
	v_sub_f32_e32 v47, v47, v36
	v_sub_f32_e32 v48, v48, v36
	v_sub_f32_e32 v49, v49, v36
	v_sub_f32_e32 v50, v50, v36
	v_sub_f32_e32 v51, v51, v36
	v_sub_f32_e32 v52, v52, v36
	v_mov_b32_e32 v36, v2
	s_branch .LBB0_2346

.LBB0_2346:
	v_lshrrev_b32_e32 v53, v132, v35
	v_bfe_i32 v54, v53, 1, 1
	v_exp_f32_e32 v38, v34
	v_bfe_i32 v231, v53, 0, 1
	v_pk_add_f32 v[34:35], v[18:19], v[92:93] op_sel_hi:[1,0] neg_lo:[0,1] neg_hi:[0,1]
	v_bfe_i32 v56, v53, 2, 1
	v_pk_add_f32 v[22:23], v[22:23], v[92:93] op_sel_hi:[1,0] neg_lo:[0,1] neg_hi:[0,1]
	v_bfi_b32 v18, v54, v35, v177
	v_bfe_i32 v55, v53, 3, 1
	v_pk_add_f32 v[24:25], v[24:25], v[92:93] op_sel_hi:[1,0] neg_lo:[0,1] neg_hi:[0,1]
	v_bfi_b32 v19, v231, v34, v177
	v_pk_add_f32 v[34:35], v[20:21], v[92:93] op_sel_hi:[1,0] neg_lo:[0,1] neg_hi:[0,1]
	v_max3_f32 v54, v19, s55, v18
	v_bfe_i32 v21, v53, 9, 1
	v_bfi_b32 v20, v55, v35, v177
	v_pk_add_f32 v[26:27], v[26:27], v[92:93] op_sel_hi:[1,0] neg_lo:[0,1] neg_hi:[0,1]
	v_pk_add_f32 v[28:29], v[28:29], v[92:93] op_sel_hi:[1,0] neg_lo:[0,1] neg_hi:[0,1]
	v_bfi_b32 v34, v56, v34, v177
	v_max3_f32 v35, v54, v34, v20
	v_bfe_i32 v232, v53, 8, 1
	v_pk_add_f32 v[30:31], v[30:31], v[92:93] op_sel_hi:[1,0] neg_lo:[0,1] neg_hi:[0,1]
	v_pk_add_f32 v[32:33], v[32:33], v[92:93] op_sel_hi:[1,0] neg_lo:[0,1] neg_hi:[0,1]
	v_bfi_b32 v21, v21, v23, v177
	v_bfe_i32 v23, v53, 11, 1
	v_bfe_i32 v233, v53, 10, 1
	v_bfi_b32 v22, v232, v22, v177
	v_max3_f32 v35, v35, v22, v21
	v_exp_f32_e32 v37, v37
	v_bfi_b32 v23, v23, v25, v177
	v_bfe_i32 v234, v53, 16, 1
	v_exp_f32_e32 v39, v39
	v_bfi_b32 v25, v233, v24, v177
	v_bfe_i32 v24, v53, 17, 1
	v_max3_f32 v35, v35, v25, v23
	v_exp_f32_e32 v40, v40
	v_bfi_b32 v24, v24, v27, v177
	v_bfe_i32 v27, v53, 19, 1
	v_bfe_i32 v235, v53, 18, 1
	v_bfi_b32 v26, v234, v26, v177
	v_max3_f32 v35, v35, v26, v24
	v_exp_f32_e32 v41, v41
	v_bfi_b32 v27, v27, v29, v177
	v_bfe_i32 v54, v53, 24, 1
	v_exp_f32_e32 v42, v42
	v_bfi_b32 v29, v235, v28, v177
	v_bfe_i32 v28, v53, 25, 1
	v_max3_f32 v35, v35, v29, v27
	v_exp_f32_e32 v43, v43
	v_bfi_b32 v28, v28, v31, v177
	v_bfe_i32 v31, v53, 27, 1
	v_bfe_i32 v53, v53, 26, 1
	v_bfi_b32 v30, v54, v30, v177
	v_max3_f32 v35, v35, v30, v28
	v_exp_f32_e32 v44, v44
	v_bfi_b32 v31, v31, v33, v177
	v_exp_f32_e32 v45, v45
	v_exp_f32_e32 v46, v46
	v_bfi_b32 v32, v53, v32, v177
	v_max3_f32 v33, v35, v32, v31
	v_mov_b32_e32 v35, v33
	v_exp_f32_e32 v47, v47
	v_exp_f32_e32 v48, v48
	v_exp_f32_e32 v49, v49
	v_exp_f32_e32 v50, v50
	v_exp_f32_e32 v51, v51
	v_exp_f32_e32 v52, v52
	v_permlane32_swap_b32_e32 v33, v35
	v_max_f32_e32 v35, v35, v35
	v_max_f32_e32 v33, v33, v33
	v_max_f32_e32 v35, v33, v35
	v_cmp_lt_f32_e64 s[0:1], s56, v35
	v_cvt_pk_bf16_f32 v86, v37, v38
	v_cvt_pk_bf16_f32 v87, v39, v40
	v_cvt_pk_bf16_f32 v88, v41, v42
	v_cvt_pk_bf16_f32 v89, v43, v44
	v_cvt_pk_bf16_f32 v82, v45, v46
	v_cvt_pk_bf16_f32 v83, v47, v48
	v_cvt_pk_bf16_f32 v84, v49, v50
	v_cvt_pk_bf16_f32 v85, v51, v52
	s_mov_b64 vcc, s[0:1]
	s_cbranch_vccz .LBB0_2348
	v_cndmask_b32_e64 v33, v178, -v35, s[0:1]
	v_exp_f32_e32 v54, v33
	v_lshlrev_b32_e32 v56, 16, v86
	v_and_b32_e32 v57, 0xffff0000, v86
	v_lshlrev_b32_e32 v58, 16, v87
	v_pk_mul_f32 v[56:57], v[54:55], v[56:57] op_sel_hi:[0,1]
	v_and_b32_e32 v59, 0xffff0000, v87
	v_cvt_pk_bf16_f32 v86, v56, v57
	v_pk_mul_f32 v[56:57], v[54:55], v[58:59] op_sel_hi:[0,1]
	v_cvt_pk_bf16_f32 v87, v56, v57
	v_lshlrev_b32_e32 v56, 16, v88
	v_and_b32_e32 v57, 0xffff0000, v88
	v_pk_mul_f32 v[56:57], v[54:55], v[56:57] op_sel_hi:[0,1]
	v_cvt_pk_bf16_f32 v88, v56, v57
	v_lshlrev_b32_e32 v56, 16, v89
	v_and_b32_e32 v57, 0xffff0000, v89
	v_pk_mul_f32 v[56:57], v[54:55], v[56:57] op_sel_hi:[0,1]
	v_cvt_pk_bf16_f32 v89, v56, v57
	v_lshlrev_b32_e32 v56, 16, v82
	v_and_b32_e32 v57, 0xffff0000, v82
	v_pk_mul_f32 v[56:57], v[54:55], v[56:57] op_sel_hi:[0,1]
	v_cvt_pk_bf16_f32 v82, v56, v57
	v_lshlrev_b32_e32 v56, 16, v83
	v_and_b32_e32 v57, 0xffff0000, v83
	v_pk_mul_f32 v[56:57], v[54:55], v[56:57] op_sel_hi:[0,1]
	v_cvt_pk_bf16_f32 v83, v56, v57
	v_lshlrev_b32_e32 v56, 16, v84
	v_and_b32_e32 v57, 0xffff0000, v84
	v_pk_mul_f32 v[56:57], v[54:55], v[56:57] op_sel_hi:[0,1]
	v_cvt_pk_bf16_f32 v84, v56, v57
	v_lshlrev_b32_e32 v56, 16, v85
	v_and_b32_e32 v57, 0xffff0000, v85
	v_pk_mul_f32 v[54:55], v[54:55], v[56:57] op_sel_hi:[0,1]
	v_cvt_pk_bf16_f32 v85, v54, v55

.LBB0_2352:
	s_add_i32 s0, s7, -2
	s_and_b32 s12, s0, 3
	s_cmp_lt_i32 s7, s64
	s_cselect_b32 s8, s59, 0
	s_cselect_b32 s9, s7, s42
	s_and_b64 s[0:1], s[40:41], exec
	s_cselect_b32 s0, s8, s9
	s_ashr_i32 s1, s0, 31
	s_lshl_b64 s[8:9], s[0:1], 18
	s_add_u32 s8, s60, s8
	s_addc_u32 s9, s61, s9
	s_add_i32 s10, s6, 0xfffe8000
	s_and_b32 s10, s10, 0x18000
	s_xor_b32 s13, s10, 0x10000
	s_lshl_b64 s[10:11], s[0:1], 7
	s_add_u32 s10, s39, s10
	s_addc_u32 s11, s62, s11
	s_add_i32 s13, s63, s13
	s_waitcnt vmcnt(5) lgkmcnt(0)
	s_barrier
	v_lshl_add_u32 v74, s12, 11, v96
	s_mov_b32 m0, s13
	ds_read_b64 v[94:95], v74
	global_load_lds_dwordx4 v152, s[8:9]
	v_lshl_add_u64 v[74:75], v[0:1], 1, s[10:11]
	s_add_i32 m0, s13, 0x4000
	s_lshl_b64 s[0:1], s[0:1], 16
	global_load_lds_dwordx4 v[74:75], off
	s_add_i32 m0, s13, 0x400
	v_lshl_add_u64 v[74:75], v[142:143], 1, s[10:11]
	global_load_lds_dwordx4 v154, s[8:9]
	s_and_b32 s8, s6, 0x18000
	s_add_i32 m0, s13, 0x4400
	s_add_i32 s8, s8, 0
	global_load_lds_dwordx4 v[74:75], off
	v_add_u32_e32 v90, s8, v147
	ds_read_b128 v[74:77], v90 offset:16384
	ds_read_b128 v[78:81], v90 offset:20480
	s_waitcnt lgkmcnt(0)
	v_mfma_f32_32x32x16_bf16 v[50:65], v[74:77], v[86:89], v[50:65]
	v_mfma_f32_32x32x16_bf16 v[34:49], v[78:81], v[86:89], v[34:49]
	ds_read_b128 v[74:77], v90 offset:24576
	ds_read_b128 v[78:81], v90 offset:28672
	s_waitcnt lgkmcnt(0)
	v_mfma_f32_32x32x16_bf16 v[18:33], v[74:77], v[86:89], v[18:33]
	v_lshl_add_u64 v[74:75], v[150:151], 0, s[0:1]
	s_and_b32 s0, s5, 0x1800
	s_xor_b32 s0, s0, 0x1000
	s_add_i32 m0, s43, s0
	s_lshl_b32 s0, s12, 15
	global_load_lds_dword v[74:75], off
	v_mfma_f32_32x32x16_bf16 v[2:17], v[78:81], v[86:89], v[2:17]
	v_add_u32_e32 v86, s8, v172
	ds_read_b128 v[74:77], v86 offset:16384
	ds_read_b128 v[78:81], v86 offset:20480
	s_add_i32 s0, s0, 0
	v_add_u32_e32 v93, s0, v149
	v_add_u32_e32 v97, s0, v165
	v_add_u32_e32 v153, s0, v168
	s_waitcnt lgkmcnt(0)
	v_mfma_f32_32x32x16_bf16 v[50:65], v[74:77], v[82:85], v[50:65]
	v_add_u32_e32 v155, s0, v169
	v_add_u32_e32 v179, s0, v170
	v_add_u32_e32 v208, s0, v171
	v_mfma_f32_32x32x16_bf16 v[34:49], v[78:81], v[82:85], v[34:49]
	ds_read_b128 v[74:77], v86 offset:24576
	ds_read_b128 v[78:81], v86 offset:28672
	s_waitcnt lgkmcnt(0)
	v_mfma_f32_32x32x16_bf16 v[18:33], v[74:77], v[82:85], v[18:33]
	v_mfma_f32_32x32x16_bf16 v[2:17], v[78:81], v[82:85], v[2:17]
	v_add_u32_e32 v82, s8, v173
	ds_read_b128 v[74:77], v82 offset:16384
	ds_read_b128 v[78:81], v82 offset:20480
	s_waitcnt lgkmcnt(0)
	v_mfma_f32_32x32x16_bf16 v[50:65], v[74:77], v[70:73], v[50:65]
	v_mfma_f32_32x32x16_bf16 v[34:49], v[78:81], v[70:73], v[34:49]
	ds_read_b128 v[74:77], v82 offset:24576
	ds_read_b128 v[78:81], v82 offset:28672
	s_waitcnt lgkmcnt(0)
	v_mfma_f32_32x32x16_bf16 v[2:17], v[78:81], v[70:73], v[2:17]
	v_add_u32_e32 v78, s8, v174
	v_mfma_f32_32x32x16_bf16 v[18:33], v[74:77], v[70:73], v[18:33]
	ds_read_b128 v[70:73], v78 offset:16384
	ds_read_b128 v[74:77], v78 offset:20480
	s_waitcnt lgkmcnt(0)
	v_mfma_f32_32x32x16_bf16 v[50:65], v[70:73], v[66:69], v[50:65]
	ds_read_b128 v[70:73], v78 offset:24576
	ds_read_b128 v[156:159], v78 offset:28672
	ds_read_b128 v[180:183], v97
	v_mfma_f32_32x32x16_bf16 v[34:49], v[74:77], v[66:69], v[34:49]
	ds_read_b128 v[74:77], v93
	s_waitcnt lgkmcnt(0)
	v_mfma_f32_32x32x16_bf16 v[76:91], v[74:77], v[98:101], 0
	v_add_u32_e32 v74, s0, v166
	v_add_u32_e32 v75, s0, v167
	ds_read_b128 v[184:187], v75
	v_mfma_f32_32x32x16_bf16 v[76:91], v[180:183], v[102:105], v[76:91]
	ds_read_b128 v[180:183], v74
	s_waitcnt lgkmcnt(0)
	v_mfma_f32_32x32x16_bf16 v[76:91], v[180:183], v[106:109], v[76:91]
	ds_read_b128 v[180:183], v153
	v_mfma_f32_32x32x16_bf16 v[76:91], v[184:187], v[110:113], v[76:91]
	ds_read_b128 v[184:187], v155
	s_waitcnt lgkmcnt(0)
	v_mfma_f32_32x32x16_bf16 v[76:91], v[180:183], v[114:117], v[76:91]
	ds_read_b128 v[180:183], v179
	v_mfma_f32_32x32x16_bf16 v[76:91], v[184:187], v[118:121], v[76:91]
	ds_read_b128 v[184:187], v208
	s_waitcnt lgkmcnt(0)
	v_mfma_f32_32x32x16_bf16 v[76:91], v[180:183], v[122:125], v[76:91]
	ds_read_b128 v[180:183], v93 offset:8192
	ds_read_b128 v[188:191], v97 offset:8192
	ds_read_b128 v[192:195], v74 offset:8192
	ds_read_b128 v[196:199], v75 offset:8192
	ds_read_b128 v[200:203], v153 offset:8192
	ds_read_b128 v[204:207], v155 offset:8192
	v_lshrrev_b32_e32 v93, v132, v94
	v_bfe_i32 v94, v93, 1, 1
	v_bfe_i32 v97, v93, 0, 1
	v_mfma_f32_32x32x16_bf16 v[76:91], v[184:187], v[126:129], v[76:91]
	ds_read_b128 v[184:187], v179 offset:8192
	ds_read_b128 v[208:211], v208 offset:8192
	v_mfma_f32_32x32x16_bf16 v[18:33], v[70:73], v[66:69], v[18:33]
	s_nop 8
	v_add_f32_e64 v74, v76, -v92
	v_add_f32_e64 v75, v77, -v92
	v_bfe_i32 v73, v93, 3, 1
	v_bfi_b32 v94, v94, v75, v177
	v_pk_add_f32 v[70:71], v[78:79], v[92:93] op_sel_hi:[1,0] neg_lo:[0,1] neg_hi:[0,1]
	v_bfi_b32 v97, v97, v74, v177
	v_bfe_i32 v74, v93, 2, 1
	v_max3_f32 v72, v97, s55, v94
	v_mfma_f32_32x32x16_bf16 v[2:17], v[156:159], v[66:69], v[2:17]
	v_bfi_b32 v153, v73, v71, v177
	v_add_f32_e64 v158, v80, -v92
	v_add_f32_e64 v159, v81, -v92
	v_bfe_i32 v156, v93, 9, 1
	v_bfi_b32 v155, v74, v70, v177
	v_max3_f32 v179, v72, v155, v153
	v_bfe_i32 v157, v93, 8, 1
	s_waitcnt lgkmcnt(0)
	v_mfma_f32_32x32x16_bf16 v[66:81], v[180:183], v[98:101], 0
	v_bfe_i32 v236, v93, 11, 1
	v_bfe_i32 v237, v93, 10, 1
	v_bfi_b32 v156, v156, v159, v177
	v_mfma_f32_32x32x16_bf16 v[66:81], v[188:191], v[102:105], v[66:81]
	v_bfi_b32 v157, v157, v158, v177
	v_add_f32_e64 v158, v82, -v92
	v_add_f32_e64 v159, v83, -v92
	v_bfe_i32 v238, v93, 17, 1
	v_max3_f32 v179, v179, v157, v156
	v_bfi_b32 v82, v236, v159, v177
	v_mfma_f32_32x32x16_bf16 v[66:81], v[192:195], v[106:109], v[66:81]
	v_bfe_i32 v239, v93, 16, 1
	v_bfi_b32 v83, v237, v158, v177
	v_add_f32_e64 v158, v84, -v92
	v_add_f32_e64 v159, v85, -v92
	v_bfe_i32 v240, v93, 19, 1
	v_max3_f32 v179, v179, v83, v82
	v_bfi_b32 v84, v238, v159, v177
	v_mfma_f32_32x32x16_bf16 v[66:81], v[196:199], v[110:113], v[66:81]
	v_bfe_i32 v241, v93, 18, 1
	v_bfi_b32 v85, v239, v158, v177
	v_add_f32_e64 v158, v86, -v92
	v_add_f32_e64 v159, v87, -v92
	v_bfe_i32 v242, v93, 25, 1
	v_mfma_f32_32x32x16_bf16 v[66:81], v[200:203], v[114:117], v[66:81]
	v_bfi_b32 v86, v240, v159, v177
	v_bfe_i32 v181, v93, 24, 1
	v_max3_f32 v179, v179, v85, v84
	v_bfi_b32 v87, v241, v158, v177
	v_pk_add_f32 v[158:159], v[88:89], v[92:93] op_sel_hi:[1,0] neg_lo:[0,1] neg_hi:[0,1]
	v_mfma_f32_32x32x16_bf16 v[66:81], v[204:207], v[118:121], v[66:81]
	v_bfe_i32 v180, v93, 27, 1
	v_bfi_b32 v88, v242, v159, v177
	v_and_b32_e32 v93, 0x4000000, v93
	v_max3_f32 v179, v179, v87, v86
	v_bfi_b32 v89, v181, v158, v177
	v_pk_add_f32 v[158:159], v[90:91], v[92:93] op_sel_hi:[1,0] neg_lo:[0,1] neg_hi:[0,1]
	v_mfma_f32_32x32x16_bf16 v[66:81], v[184:187], v[122:125], v[66:81]
	v_max3_f32 v179, v179, v89, v88
	v_bfi_b32 v90, v180, v159, v177
	v_cmp_ne_u32_e32 vcc, 0, v93
	v_mfma_f32_32x32x16_bf16 v[66:81], v[208:211], v[126:129], v[66:81]
	s_nop 0
	v_cndmask_b32_e32 v91, v177, v158, vcc
	v_max3_f32 v93, v179, v91, v90
	v_mov_b32_e32 v158, v93
	s_nop 1
	v_permlane32_swap_b32_e32 v93, v158
	v_max_f32_e32 v93, v93, v158
	v_cmp_lt_f32_e32 vcc, s56, v93
	s_cbranch_vccz .LBB0_2354
	s_nop 0
	v_cndmask_b32_e32 v93, 0, v93, vcc
	v_exp_f32_e64 v158, -v93
	v_add_f32_e32 v92, v92, v93
	v_sub_f32_e32 v97, v97, v93
	v_sub_f32_e32 v94, v94, v93
	v_pk_mul_f32 v[64:65], v[64:65], v[158:159] op_sel_hi:[1,0]
	v_pk_mul_f32 v[62:63], v[62:63], v[158:159] op_sel_hi:[1,0]
	v_pk_mul_f32 v[60:61], v[60:61], v[158:159] op_sel_hi:[1,0]
	v_pk_mul_f32 v[58:59], v[58:59], v[158:159] op_sel_hi:[1,0]
	v_pk_mul_f32 v[56:57], v[56:57], v[158:159] op_sel_hi:[1,0]
	v_pk_mul_f32 v[54:55], v[54:55], v[158:159] op_sel_hi:[1,0]
	v_pk_mul_f32 v[52:53], v[52:53], v[158:159] op_sel_hi:[1,0]
	v_pk_mul_f32 v[50:51], v[50:51], v[158:159] op_sel_hi:[1,0]
	v_pk_mul_f32 v[48:49], v[48:49], v[158:159] op_sel_hi:[1,0]
	v_pk_mul_f32 v[46:47], v[46:47], v[158:159] op_sel_hi:[1,0]
	v_pk_mul_f32 v[44:45], v[44:45], v[158:159] op_sel_hi:[1,0]
	v_pk_mul_f32 v[42:43], v[42:43], v[158:159] op_sel_hi:[1,0]
	v_pk_mul_f32 v[40:41], v[40:41], v[158:159] op_sel_hi:[1,0]
	v_pk_mul_f32 v[38:39], v[38:39], v[158:159] op_sel_hi:[1,0]
	v_pk_mul_f32 v[36:37], v[36:37], v[158:159] op_sel_hi:[1,0]
	v_pk_mul_f32 v[34:35], v[34:35], v[158:159] op_sel_hi:[1,0]
	v_pk_mul_f32 v[32:33], v[32:33], v[158:159] op_sel_hi:[1,0]
	v_pk_mul_f32 v[30:31], v[30:31], v[158:159] op_sel_hi:[1,0]
	v_pk_mul_f32 v[28:29], v[28:29], v[158:159] op_sel_hi:[1,0]
	v_pk_mul_f32 v[26:27], v[26:27], v[158:159] op_sel_hi:[1,0]
	v_pk_mul_f32 v[24:25], v[24:25], v[158:159] op_sel_hi:[1,0]
	v_pk_mul_f32 v[22:23], v[22:23], v[158:159] op_sel_hi:[1,0]
	v_pk_mul_f32 v[20:21], v[20:21], v[158:159] op_sel_hi:[1,0]
	v_pk_mul_f32 v[18:19], v[18:19], v[158:159] op_sel_hi:[1,0]
	v_pk_mul_f32 v[16:17], v[16:17], v[158:159] op_sel_hi:[1,0]
	v_pk_mul_f32 v[14:15], v[14:15], v[158:159] op_sel_hi:[1,0]
	v_pk_mul_f32 v[12:13], v[12:13], v[158:159] op_sel_hi:[1,0]
	v_pk_mul_f32 v[10:11], v[10:11], v[158:159] op_sel_hi:[1,0]
	v_pk_mul_f32 v[8:9], v[8:9], v[158:159] op_sel_hi:[1,0]
	v_pk_mul_f32 v[6:7], v[6:7], v[158:159] op_sel_hi:[1,0]
	v_pk_mul_f32 v[4:5], v[4:5], v[158:159] op_sel_hi:[1,0]
	v_pk_mul_f32 v[2:3], v[2:3], v[158:159] op_sel_hi:[1,0]
	v_sub_f32_e32 v155, v155, v93
	v_sub_f32_e32 v153, v153, v93
	v_sub_f32_e32 v157, v157, v93
	v_sub_f32_e32 v156, v156, v93
	v_sub_f32_e32 v83, v83, v93
	v_sub_f32_e32 v82, v82, v93
	v_sub_f32_e32 v85, v85, v93
	v_sub_f32_e32 v84, v84, v93
	v_sub_f32_e32 v87, v87, v93
	v_sub_f32_e32 v86, v86, v93
	v_sub_f32_e32 v89, v89, v93
	v_sub_f32_e32 v88, v88, v93
	v_sub_f32_e32 v91, v91, v93
	v_sub_f32_e32 v90, v90, v93
	v_mul_f32_e32 v139, v139, v158
.LBB0_2354:
	v_lshrrev_b32_e32 v95, v132, v95
	v_mov_b32_e32 v93, v92
	v_exp_f32_e32 v185, v90
	v_bfe_i32 v243, v95, 1, 1
	v_bfe_i32 v188, v95, 0, 1
	v_pk_add_f32 v[186:187], v[66:67], v[92:93] neg_lo:[0,1] neg_hi:[0,1]
	v_bfe_i32 v90, v95, 3, 1
	v_bfe_i32 v189, v95, 2, 1
	v_bfi_b32 v66, v243, v187, v177
	v_pk_add_f32 v[70:71], v[70:71], v[92:93] neg_lo:[0,1] neg_hi:[0,1]
	v_pk_add_f32 v[72:73], v[72:73], v[92:93] neg_lo:[0,1] neg_hi:[0,1]
	v_bfi_b32 v67, v188, v186, v177
	v_pk_add_f32 v[186:187], v[68:69], v[92:93] neg_lo:[0,1] neg_hi:[0,1]
	v_bfe_i32 v69, v95, 9, 1
	v_pk_add_f32 v[74:75], v[74:75], v[92:93] neg_lo:[0,1] neg_hi:[0,1]
	v_bfi_b32 v68, v90, v187, v177
	v_bfe_i32 v244, v95, 8, 1
	v_pk_add_f32 v[76:77], v[76:77], v[92:93] neg_lo:[0,1] neg_hi:[0,1]
	v_bfi_b32 v90, v189, v186, v177
	v_max3_f32 v188, v67, s55, v66
	v_max3_f32 v186, v188, v90, v68
	v_bfi_b32 v69, v69, v71, v177
	v_bfe_i32 v71, v95, 11, 1
	v_bfe_i32 v245, v95, 10, 1
	v_bfi_b32 v70, v244, v70, v177
	v_max3_f32 v186, v186, v70, v69
	v_pk_add_f32 v[78:79], v[78:79], v[92:93] neg_lo:[0,1] neg_hi:[0,1]
	v_bfi_b32 v71, v71, v73, v177
	v_bfe_i32 v246, v95, 16, 1
	v_pk_add_f32 v[80:81], v[80:81], v[92:93] neg_lo:[0,1] neg_hi:[0,1]
	v_bfi_b32 v73, v245, v72, v177
	v_bfe_i32 v72, v95, 17, 1
	v_max3_f32 v186, v186, v73, v71
	v_exp_f32_e32 v97, v97
	v_bfi_b32 v72, v72, v75, v177
	v_bfe_i32 v75, v95, 19, 1
	v_bfe_i32 v247, v95, 18, 1
	v_bfi_b32 v74, v246, v74, v177
	v_max3_f32 v186, v186, v74, v72
	v_exp_f32_e32 v94, v94
	v_bfi_b32 v75, v75, v77, v177
	v_bfe_i32 v187, v95, 24, 1
	v_exp_f32_e32 v155, v155
	v_bfi_b32 v77, v247, v76, v177
	v_bfe_i32 v76, v95, 25, 1
	v_max3_f32 v186, v186, v77, v75
	v_exp_f32_e32 v153, v153
	v_bfi_b32 v76, v76, v79, v177
	v_bfe_i32 v79, v95, 27, 1
	v_bfe_i32 v95, v95, 26, 1
	v_bfi_b32 v78, v187, v78, v177
	v_max3_f32 v186, v186, v78, v76
	v_exp_f32_e32 v157, v157
	v_bfi_b32 v79, v79, v81, v177
	v_exp_f32_e32 v156, v156
	v_exp_f32_e32 v158, v83
	v_bfi_b32 v80, v95, v80, v177
	v_max3_f32 v81, v186, v80, v79
	v_mov_b32_e32 v93, v81
	v_exp_f32_e32 v159, v82
	v_exp_f32_e32 v179, v85
	v_exp_f32_e32 v180, v84
	v_exp_f32_e32 v181, v87
	v_exp_f32_e32 v182, v86
	v_exp_f32_e32 v183, v89
	v_exp_f32_e32 v184, v88
	v_exp_f32_e32 v91, v91
	v_permlane32_swap_b32_e32 v81, v93
	v_max_f32_e32 v93, v93, v93
	v_max_f32_e32 v81, v81, v81
	v_max_f32_e32 v93, v81, v93
	v_cmp_lt_f32_e64 s[0:1], s56, v93
	v_cvt_pk_bf16_f32 v86, v97, v94
	v_cvt_pk_bf16_f32 v87, v155, v153
	v_cvt_pk_bf16_f32 v88, v157, v156
	v_cvt_pk_bf16_f32 v89, v158, v159
	v_cvt_pk_bf16_f32 v82, v179, v180
	v_cvt_pk_bf16_f32 v83, v181, v182
	v_cvt_pk_bf16_f32 v84, v183, v184
	v_cvt_pk_bf16_f32 v85, v91, v185
	s_mov_b64 vcc, s[0:1]
	s_cbranch_vccz .LBB0_2356
	v_cndmask_b32_e64 v81, v178, -v93, s[0:1]
	v_exp_f32_e32 v186, v81
	v_lshlrev_b32_e32 v188, 16, v86
	v_and_b32_e32 v189, 0xffff0000, v86
	v_lshlrev_b32_e32 v190, 16, v87
	v_pk_mul_f32 v[188:189], v[186:187], v[188:189] op_sel_hi:[0,1]
	v_and_b32_e32 v191, 0xffff0000, v87
	v_cvt_pk_bf16_f32 v86, v188, v189
	v_pk_mul_f32 v[188:189], v[186:187], v[190:191] op_sel_hi:[0,1]
	v_cvt_pk_bf16_f32 v87, v188, v189
	v_lshlrev_b32_e32 v188, 16, v88
	v_and_b32_e32 v189, 0xffff0000, v88
	v_pk_mul_f32 v[188:189], v[186:187], v[188:189] op_sel_hi:[0,1]
	v_cvt_pk_bf16_f32 v88, v188, v189
	v_lshlrev_b32_e32 v188, 16, v89
	v_and_b32_e32 v189, 0xffff0000, v89
	v_pk_mul_f32 v[188:189], v[186:187], v[188:189] op_sel_hi:[0,1]
	v_cvt_pk_bf16_f32 v89, v188, v189
	v_lshlrev_b32_e32 v188, 16, v82
	v_and_b32_e32 v189, 0xffff0000, v82
	v_pk_mul_f32 v[188:189], v[186:187], v[188:189] op_sel_hi:[0,1]
	v_cvt_pk_bf16_f32 v82, v188, v189
	v_lshlrev_b32_e32 v188, 16, v83
	v_and_b32_e32 v189, 0xffff0000, v83
	v_pk_mul_f32 v[188:189], v[186:187], v[188:189] op_sel_hi:[0,1]
	v_cvt_pk_bf16_f32 v83, v188, v189
	v_lshlrev_b32_e32 v188, 16, v84
	v_and_b32_e32 v189, 0xffff0000, v84
	v_pk_mul_f32 v[188:189], v[186:187], v[188:189] op_sel_hi:[0,1]
	v_cvt_pk_bf16_f32 v84, v188, v189
	v_lshlrev_b32_e32 v188, 16, v85
	v_and_b32_e32 v189, 0xffff0000, v85
	v_pk_mul_f32 v[186:187], v[186:187], v[188:189] op_sel_hi:[0,1]
	v_cvt_pk_bf16_f32 v85, v186, v187
